# v28: v18 plus back-edge rotation in the GU GEMM loop: K-step counter and pointer updates moved from after the loop-back barrier into the end of the last load segment
# baseline (speedup 1.0000x reference)
; #define PG8_STAGE(bufoff, gbase, voff) do { _Pragma("unroll") for (int _i = 0; _i < 2; ++_i) \
;         __builtin_amdgcn_global_load_lds((const unsigned*)((const char*)(gbase) + (voff)[_i]), (PG8_LAS unsigned*)(lds + (bufoff) + ldsw + _i * 8192), 16, 0, 0); } while (0)
; #define PG8_LDA(dst, b, h) do { _Pragma("unroll") for (int m = 0; m < 4; ++m) _Pragma("unroll") for (int k = 0; k < 2; ++k) dst[m][k] = *(const PG8_LAS bf16x8*)(lds + PG8_SA(b, h) + aoff + m * 2048 + k * 1024); } while (0)
; #define PG8_LDB(dst, b, h) do { _Pragma("unroll") for (int n = 0; n < 2; ++n) _Pragma("unroll") for (int k = 0; k < 2; ++k) dst[n][k] = *(const PG8_LAS bf16x8*)(lds + PG8_SB(b, h) + boff + n * 2048 + k * 1024); } while (0)
; #define PG8_MMA(ai, bj, At, Bt) do { __builtin_amdgcn_s_setprio(1); _Pragma("unroll") for (int m = 0; m < 4; ++m) _Pragma("unroll") for (int n = 0; n < 2; ++n) _Pragma("unroll") for (int k = 0; k < 2; ++k) \
;         acc[ai][bj][m][n] = __builtin_amdgcn_mfma_f32_16x16x32_bf16(Bt[n][k], At[m][k], acc[ai][bj][m][n], 0, 0, 0); __builtin_amdgcn_s_setprio(0); } while (0)
; #define PG8_WAIT_V(n) asm volatile("s_waitcnt vmcnt(" #n ")" ::: "memory")
; #define PG8_BAR __builtin_amdgcn_s_barrier()
; template <class Epi, class Sched, bool ALIGN_EPI = false, bool SP2 = false>
; __device__ __forceinline__ void gemm_phase(PG8_LAS unsigned char* lds, const Gemm g, const Sched& S, const Epi& E, const int wid) {
;     ...
;         for (int t = 0; t < nt; t += 2) {
;             const bool last = (t == nt - 2);
;             const char* a1 = cA + (size_t)(t + 1) * kstep;
;             const char* a2 = last ? nA : cA + (size_t)(t + 2) * kstep; const char* b2 = last ? nB : cB + (size_t)(t + 2) * kstep;
;             const char* a3 = a2 + kstep; const char* b3 = b2 + kstep;
;             if (last && has_next) S.a_ready(nxt);
;             if constexpr (SP2) {
;             PG8_LDB(B0, 0, 0); PG8_LDB(B1, 0, 1); PG8_SCHED; PG8_LDA(At, 0, 0); PG8_STAGE(PG8_SA(1, 1), a1 + hstep, voffA);
;             PG8_WAIT_V(8); PG8_WAIT_L(0); PG8_BAR; PG8_MMA(0, 0, At, B0); PG8_MMA(0, 1, At, B1); PG8_BAR; PG8_SCHED;
;             PG8_LDA(At, 0, 1); PG8_STAGE(PG8_SB(0, 0), b2, voffB); PG8_STAGE(PG8_SB(0, 1), b2 + hstep, voffB); PG8_STAGE(PG8_SA(0, 0), a2, voffA);
;             PG8_WAIT_V(8); PG8_WAIT_L(0); PG8_BAR; PG8_MMA(1, 0, At, B0); PG8_MMA(1, 1, At, B1); PG8_BAR; PG8_SCHED;
.LBB0_634:
	s_add_u32 s34, s30, 0xfff80080
	s_addc_u32 s35, s31, -1
	s_add_i32 s54, 0, 0x10000
	s_cmp_eq_u32 s50, 28
	s_cselect_b32 s37, s19, s35
	s_cselect_b32 s36, s23, s34
	v_add_u32_e32 v0, s54, v149
	s_cselect_b32 s35, s21, s47
	s_cselect_b32 s34, s29, s46
	s_add_i32 s60, 0, 0x14000
	ds_read_b128 v[142:145], v0
	ds_read_b128 v[152:155], v0 offset:1024
	ds_read_b128 v[156:159], v0 offset:2048
	ds_read_b128 v[160:163], v0 offset:3072
	v_add_u32_e32 v0, s60, v149
	ds_read_b128 v[164:167], v0
	ds_read_b128 v[168:171], v0 offset:1024
	ds_read_b128 v[172:175], v0 offset:2048
	ds_read_b128 v[176:179], v0 offset:3072
	v_lshl_add_u64 v[146:147], s[30:31], 0, v[138:139]
	s_add_i32 m0, s44, 0xc000
	ds_read_b128 v[180:183], v150
	ds_read_b128 v[184:187], v150 offset:1024
	ds_read_b128 v[188:191], v150 offset:2048
	ds_read_b128 v[192:195], v150 offset:3072
	ds_read_b128 v[212:215], v150 offset:4096
	ds_read_b128 v[216:219], v150 offset:5120
	ds_read_b128 v[220:223], v150 offset:6144
	ds_read_b128 v[224:227], v150 offset:7168
	global_load_lds_dwordx4 v[146:147], off
	v_lshl_add_u64 v[146:147], s[30:31], 0, v[140:141]
	s_add_i32 m0, s44, 0xe000
	s_nop 0
	global_load_lds_dwordx4 v[146:147], off
	s_waitcnt vmcnt(8)
	s_waitcnt lgkmcnt(0)
	s_barrier
	s_setprio 1
	s_waitcnt lgkmcnt(0)
	v_mfma_f32_16x16x32_bf16 v[126:129], v[142:145], v[180:183], v[126:129]
	v_mfma_f32_16x16x32_bf16 v[122:125], v[156:159], v[180:183], v[122:125]
	v_mfma_f32_16x16x32_bf16 v[110:113], v[142:145], v[188:191], v[110:113]
	v_mfma_f32_16x16x32_bf16 v[106:109], v[156:159], v[188:191], v[106:109]
	v_mfma_f32_16x16x32_bf16 v[94:97], v[142:145], v[212:215], v[94:97]
	v_mfma_f32_16x16x32_bf16 v[90:93], v[156:159], v[212:215], v[90:93]
	v_mfma_f32_16x16x32_bf16 v[78:81], v[142:145], v[220:223], v[78:81]
	v_mfma_f32_16x16x32_bf16 v[74:77], v[156:159], v[220:223], v[74:77]
	v_mfma_f32_16x16x32_bf16 v[126:129], v[152:155], v[184:187], v[126:129]
	v_mfma_f32_16x16x32_bf16 v[122:125], v[160:163], v[184:187], v[122:125]
	v_mfma_f32_16x16x32_bf16 v[110:113], v[152:155], v[192:195], v[110:113]
	v_mfma_f32_16x16x32_bf16 v[106:109], v[160:163], v[192:195], v[106:109]
	v_mfma_f32_16x16x32_bf16 v[94:97], v[152:155], v[216:219], v[94:97]
	v_mfma_f32_16x16x32_bf16 v[90:93], v[160:163], v[216:219], v[90:93]
	v_mfma_f32_16x16x32_bf16 v[78:81], v[152:155], v[224:227], v[78:81]
	v_mfma_f32_16x16x32_bf16 v[74:77], v[160:163], v[224:227], v[74:77]
	s_setprio 0
	s_setprio 1
	v_mfma_f32_16x16x32_bf16 v[118:121], v[164:167], v[180:183], v[118:121]
	v_mfma_f32_16x16x32_bf16 v[114:117], v[172:175], v[180:183], v[114:117]
	v_mfma_f32_16x16x32_bf16 v[102:105], v[164:167], v[188:191], v[102:105]
	v_mfma_f32_16x16x32_bf16 v[98:101], v[172:175], v[188:191], v[98:101]
	v_mfma_f32_16x16x32_bf16 v[86:89], v[164:167], v[212:215], v[86:89]
	v_mfma_f32_16x16x32_bf16 v[82:85], v[172:175], v[212:215], v[82:85]
	v_mfma_f32_16x16x32_bf16 v[70:73], v[164:167], v[220:223], v[70:73]
	v_mfma_f32_16x16x32_bf16 v[66:69], v[172:175], v[220:223], v[66:69]
	v_mfma_f32_16x16x32_bf16 v[118:121], v[168:171], v[184:187], v[118:121]
	v_mfma_f32_16x16x32_bf16 v[114:117], v[176:179], v[184:187], v[114:117]
	v_mfma_f32_16x16x32_bf16 v[102:105], v[168:171], v[192:195], v[102:105]
	v_mfma_f32_16x16x32_bf16 v[98:101], v[176:179], v[192:195], v[98:101]
	v_mfma_f32_16x16x32_bf16 v[86:89], v[168:171], v[216:219], v[86:89]
	v_mfma_f32_16x16x32_bf16 v[82:85], v[176:179], v[216:219], v[82:85]
	v_mfma_f32_16x16x32_bf16 v[70:73], v[168:171], v[224:227], v[70:73]
	v_mfma_f32_16x16x32_bf16 v[66:69], v[176:179], v[224:227], v[66:69]
	s_setprio 0
	s_barrier
	s_add_i32 s54, s54, s42
	v_lshl_add_u64 v[146:147], s[34:35], 0, v[134:135]
	s_mov_b32 m0, s54
	ds_read_b128 v[180:183], v150 offset:16384
	ds_read_b128 v[184:187], v150 offset:17408
	ds_read_b128 v[188:191], v150 offset:18432
	ds_read_b128 v[192:195], v150 offset:19456
	ds_read_b128 v[212:215], v150 offset:20480
	ds_read_b128 v[216:219], v150 offset:21504
	ds_read_b128 v[220:223], v150 offset:22528
	ds_read_b128 v[224:227], v150 offset:23552
	global_load_lds_dwordx4 v[146:147], off
	s_add_i32 m0, s54, 0x2000
	s_add_u32 s54, s34, 0x80000
	v_lshl_add_u64 v[200:201], s[34:35], 0, v[130:131]
	s_addc_u32 s55, s35, 0
	s_add_i32 s60, s60, s42
	global_load_lds_dwordx4 v[200:201], off
	v_lshl_add_u64 v[202:203], s[54:55], 0, v[134:135]
	s_mov_b32 m0, s60
	v_lshl_add_u64 v[208:209], s[36:37], 0, v[132:133]
	global_load_lds_dwordx4 v[202:203], off
	v_lshl_add_u64 v[202:203], s[54:55], 0, v[130:131]
	s_add_i32 m0, s60, 0x2000
	s_nop 0
	global_load_lds_dwordx4 v[202:203], off
	v_lshl_add_u64 v[202:203], s[36:37], 0, v[136:137]
	s_mov_b32 m0, s44
	s_nop 0
	global_load_lds_dwordx4 v[202:203], off
	s_mov_b32 m0, s45
	s_nop 0
	global_load_lds_dwordx4 v[208:209], off
	s_waitcnt vmcnt(8)
	s_waitcnt lgkmcnt(0)
	s_barrier
; #define PG8_STAGE(bufoff, gbase, voff) do { _Pragma("unroll") for (int _i = 0; _i < 2; ++_i) \
;         __builtin_amdgcn_global_load_lds((const unsigned*)((const char*)(gbase) + (voff)[_i]), (PG8_LAS unsigned*)(lds + (bufoff) + ldsw + _i * 8192), 16, 0, 0); } while (0)
; #define PG8_LDA(dst, b, h) do { _Pragma("unroll") for (int m = 0; m < 4; ++m) _Pragma("unroll") for (int k = 0; k < 2; ++k) dst[m][k] = *(const PG8_LAS bf16x8*)(lds + PG8_SA(b, h) + aoff + m * 2048 + k * 1024); } while (0)
; #define PG8_LDB(dst, b, h) do { _Pragma("unroll") for (int n = 0; n < 2; ++n) _Pragma("unroll") for (int k = 0; k < 2; ++k) dst[n][k] = *(const PG8_LAS bf16x8*)(lds + PG8_SB(b, h) + boff + n * 2048 + k * 1024); } while (0)
; #define PG8_MMA(ai, bj, At, Bt) do { __builtin_amdgcn_s_setprio(1); _Pragma("unroll") for (int m = 0; m < 4; ++m) _Pragma("unroll") for (int n = 0; n < 2; ++n) _Pragma("unroll") for (int k = 0; k < 2; ++k) \
;         acc[ai][bj][m][n] = __builtin_amdgcn_mfma_f32_16x16x32_bf16(Bt[n][k], At[m][k], acc[ai][bj][m][n], 0, 0, 0); __builtin_amdgcn_s_setprio(0); } while (0)
; #define PG8_WAIT_V(n) asm volatile("s_waitcnt vmcnt(" #n ")" ::: "memory")
; #define PG8_WAIT_L(n) asm volatile("s_waitcnt lgkmcnt(" #n ")" ::: "memory")
; #define PG8_BAR __builtin_amdgcn_s_barrier()
; #define PG8_SCHED __builtin_amdgcn_sched_barrier(0)
; template <class Epi, class Sched, bool ALIGN_EPI = false, bool SP2 = false>
; __device__ __forceinline__ void gemm_phase(PG8_LAS unsigned char* lds, const Gemm g, const Sched& S, const Epi& E, const int wid) {
;     ...
;             PG8_WAIT_V(8); PG8_WAIT_L(0); PG8_BAR; PG8_MMA(1, 0, At, B0); PG8_MMA(1, 1, At, B1); PG8_BAR; PG8_SCHED;
;             PG8_LDB(B0, 1, 0); PG8_LDB(B1, 1, 1); PG8_SCHED; PG8_LDA(At, 1, 0); PG8_STAGE(PG8_SA(0, 1), a2 + hstep, voffA);
;             PG8_WAIT_V(8); PG8_WAIT_L(0); PG8_BAR; PG8_MMA(0, 0, At, B0); PG8_MMA(0, 1, At, B1); PG8_BAR; PG8_SCHED;
	s_setprio 1
	s_waitcnt lgkmcnt(0)
	v_mfma_f32_16x16x32_bf16 v[62:65], v[142:145], v[180:183], v[62:65]
	v_mfma_f32_16x16x32_bf16 v[58:61], v[156:159], v[180:183], v[58:61]
	v_mfma_f32_16x16x32_bf16 v[46:49], v[142:145], v[188:191], v[46:49]
	v_mfma_f32_16x16x32_bf16 v[42:45], v[156:159], v[188:191], v[42:45]
	v_mfma_f32_16x16x32_bf16 v[30:33], v[142:145], v[212:215], v[30:33]
	v_mfma_f32_16x16x32_bf16 v[26:29], v[156:159], v[212:215], v[26:29]
	v_mfma_f32_16x16x32_bf16 v[14:17], v[142:145], v[220:223], v[14:17]
	v_mfma_f32_16x16x32_bf16 v[10:13], v[156:159], v[220:223], v[10:13]
	v_mfma_f32_16x16x32_bf16 v[62:65], v[152:155], v[184:187], v[62:65]
	v_mfma_f32_16x16x32_bf16 v[58:61], v[160:163], v[184:187], v[58:61]
	v_mfma_f32_16x16x32_bf16 v[46:49], v[152:155], v[192:195], v[46:49]
	v_mfma_f32_16x16x32_bf16 v[42:45], v[160:163], v[192:195], v[42:45]
	v_mfma_f32_16x16x32_bf16 v[30:33], v[152:155], v[216:219], v[30:33]
	v_mfma_f32_16x16x32_bf16 v[26:29], v[160:163], v[216:219], v[26:29]
	v_mfma_f32_16x16x32_bf16 v[14:17], v[152:155], v[224:227], v[14:17]
	v_mfma_f32_16x16x32_bf16 v[10:13], v[160:163], v[224:227], v[10:13]
	s_setprio 0
	s_setprio 1
	v_mfma_f32_16x16x32_bf16 v[54:57], v[164:167], v[180:183], v[54:57]
	v_mfma_f32_16x16x32_bf16 v[50:53], v[172:175], v[180:183], v[50:53]
	v_mfma_f32_16x16x32_bf16 v[38:41], v[164:167], v[188:191], v[38:41]
	v_mfma_f32_16x16x32_bf16 v[34:37], v[172:175], v[188:191], v[34:37]
	v_mfma_f32_16x16x32_bf16 v[22:25], v[164:167], v[212:215], v[22:25]
	v_mfma_f32_16x16x32_bf16 v[18:21], v[172:175], v[212:215], v[18:21]
	v_mfma_f32_16x16x32_bf16 v[6:9], v[164:167], v[220:223], v[6:9]
	v_mfma_f32_16x16x32_bf16 v[2:5], v[172:175], v[220:223], v[2:5]
	v_mfma_f32_16x16x32_bf16 v[54:57], v[168:171], v[184:187], v[54:57]
	v_mfma_f32_16x16x32_bf16 v[50:53], v[176:179], v[184:187], v[50:53]
	v_mfma_f32_16x16x32_bf16 v[38:41], v[168:171], v[192:195], v[38:41]
	v_mfma_f32_16x16x32_bf16 v[34:37], v[176:179], v[192:195], v[34:37]
	v_mfma_f32_16x16x32_bf16 v[22:25], v[168:171], v[216:219], v[22:25]
	v_mfma_f32_16x16x32_bf16 v[18:21], v[176:179], v[216:219], v[18:21]
	v_mfma_f32_16x16x32_bf16 v[6:9], v[168:171], v[224:227], v[6:9]
	v_mfma_f32_16x16x32_bf16 v[2:5], v[176:179], v[224:227], v[2:5]
	s_setprio 0
	s_barrier
	s_add_i32 s54, 0, 0x18000
	v_add_u32_e32 v0, s54, v149
	s_add_i32 s55, 0, 0x1c000
	ds_read_b128 v[142:145], v0
	ds_read_b128 v[152:155], v0 offset:1024
	ds_read_b128 v[156:159], v0 offset:2048
	ds_read_b128 v[160:163], v0 offset:3072
	v_add_u32_e32 v0, s55, v149
	ds_read_b128 v[164:167], v0
	ds_read_b128 v[168:171], v0 offset:1024
	ds_read_b128 v[172:175], v0 offset:2048
	ds_read_b128 v[176:179], v0 offset:3072
	s_add_u32 s36, s36, 0x80000
	s_addc_u32 s37, s37, 0
	s_mov_b32 m0, s52
	v_lshl_add_u64 v[210:211], s[36:37], 0, v[136:137]
	ds_read_b128 v[180:183], v150 offset:32768
	ds_read_b128 v[184:187], v150 offset:33792
	ds_read_b128 v[188:191], v150 offset:34816
	ds_read_b128 v[192:195], v150 offset:35840
	ds_read_b128 v[212:215], v150 offset:36864
	ds_read_b128 v[216:219], v150 offset:37888
	ds_read_b128 v[220:223], v150 offset:38912
	ds_read_b128 v[224:227], v150 offset:39936
	global_load_lds_dwordx4 v[210:211], off
	v_lshl_add_u64 v[210:211], s[36:37], 0, v[132:133]
	s_mov_b32 m0, s68
	s_nop 0
	global_load_lds_dwordx4 v[210:211], off
	s_waitcnt vmcnt(8)
	s_waitcnt lgkmcnt(0)
	s_barrier
	s_setprio 1
	s_waitcnt lgkmcnt(0)
	v_mfma_f32_16x16x32_bf16 v[126:129], v[142:145], v[180:183], v[126:129]
	v_mfma_f32_16x16x32_bf16 v[122:125], v[156:159], v[180:183], v[122:125]
	v_mfma_f32_16x16x32_bf16 v[110:113], v[142:145], v[188:191], v[110:113]
	v_mfma_f32_16x16x32_bf16 v[106:109], v[156:159], v[188:191], v[106:109]
	v_mfma_f32_16x16x32_bf16 v[94:97], v[142:145], v[212:215], v[94:97]
	v_mfma_f32_16x16x32_bf16 v[90:93], v[156:159], v[212:215], v[90:93]
	v_mfma_f32_16x16x32_bf16 v[78:81], v[142:145], v[220:223], v[78:81]
	v_mfma_f32_16x16x32_bf16 v[74:77], v[156:159], v[220:223], v[74:77]
	v_mfma_f32_16x16x32_bf16 v[126:129], v[152:155], v[184:187], v[126:129]
	v_mfma_f32_16x16x32_bf16 v[122:125], v[160:163], v[184:187], v[122:125]
	v_mfma_f32_16x16x32_bf16 v[110:113], v[152:155], v[192:195], v[110:113]
	v_mfma_f32_16x16x32_bf16 v[106:109], v[160:163], v[192:195], v[106:109]
	v_mfma_f32_16x16x32_bf16 v[94:97], v[152:155], v[216:219], v[94:97]
	v_mfma_f32_16x16x32_bf16 v[90:93], v[160:163], v[216:219], v[90:93]
	v_mfma_f32_16x16x32_bf16 v[78:81], v[152:155], v[224:227], v[78:81]
	v_mfma_f32_16x16x32_bf16 v[74:77], v[160:163], v[224:227], v[74:77]
	s_setprio 0
	s_setprio 1
	v_mfma_f32_16x16x32_bf16 v[118:121], v[164:167], v[180:183], v[118:121]
	v_mfma_f32_16x16x32_bf16 v[114:117], v[172:175], v[180:183], v[114:117]
	v_mfma_f32_16x16x32_bf16 v[102:105], v[164:167], v[188:191], v[102:105]
	v_mfma_f32_16x16x32_bf16 v[98:101], v[172:175], v[188:191], v[98:101]
	v_mfma_f32_16x16x32_bf16 v[86:89], v[164:167], v[212:215], v[86:89]
	v_mfma_f32_16x16x32_bf16 v[82:85], v[172:175], v[212:215], v[82:85]
	v_mfma_f32_16x16x32_bf16 v[70:73], v[164:167], v[220:223], v[70:73]
	v_mfma_f32_16x16x32_bf16 v[66:69], v[172:175], v[220:223], v[66:69]
	v_mfma_f32_16x16x32_bf16 v[118:121], v[168:171], v[184:187], v[118:121]
	v_mfma_f32_16x16x32_bf16 v[114:117], v[176:179], v[184:187], v[114:117]
	v_mfma_f32_16x16x32_bf16 v[102:105], v[168:171], v[192:195], v[102:105]
	v_mfma_f32_16x16x32_bf16 v[98:101], v[176:179], v[192:195], v[98:101]
	v_mfma_f32_16x16x32_bf16 v[86:89], v[168:171], v[216:219], v[86:89]
	v_mfma_f32_16x16x32_bf16 v[82:85], v[176:179], v[216:219], v[82:85]
	v_mfma_f32_16x16x32_bf16 v[70:73], v[168:171], v[224:227], v[70:73]
	v_mfma_f32_16x16x32_bf16 v[66:69], v[176:179], v[224:227], v[66:69]
	s_setprio 0
	s_barrier
; #define PG8_STAGE(bufoff, gbase, voff) do { _Pragma("unroll") for (int _i = 0; _i < 2; ++_i) \
;         __builtin_amdgcn_global_load_lds((const unsigned*)((const char*)(gbase) + (voff)[_i]), (PG8_LAS unsigned*)(lds + (bufoff) + ldsw + _i * 8192), 16, 0, 0); } while (0)
; #define PG8_LDA(dst, b, h) do { _Pragma("unroll") for (int m = 0; m < 4; ++m) _Pragma("unroll") for (int k = 0; k < 2; ++k) dst[m][k] = *(const PG8_LAS bf16x8*)(lds + PG8_SA(b, h) + aoff + m * 2048 + k * 1024); } while (0)
; #define PG8_MMA(ai, bj, At, Bt) do { __builtin_amdgcn_s_setprio(1); _Pragma("unroll") for (int m = 0; m < 4; ++m) _Pragma("unroll") for (int n = 0; n < 2; ++n) _Pragma("unroll") for (int k = 0; k < 2; ++k) \
;         acc[ai][bj][m][n] = __builtin_amdgcn_mfma_f32_16x16x32_bf16(Bt[n][k], At[m][k], acc[ai][bj][m][n], 0, 0, 0); __builtin_amdgcn_s_setprio(0); } while (0)
; #define PG8_WAIT_V(n) asm volatile("s_waitcnt vmcnt(" #n ")" ::: "memory")
; #define PG8_WAIT_L(n) asm volatile("s_waitcnt lgkmcnt(" #n ")" ::: "memory")
; #define PG8_BAR __builtin_amdgcn_s_barrier()
; #define PG8_SCHED __builtin_amdgcn_sched_barrier(0)
; template <class Epi, class Sched, bool ALIGN_EPI = false, bool SP2 = false>
; __device__ __forceinline__ void gemm_phase(PG8_LAS unsigned char* lds, const Gemm g, const Sched& S, const Epi& E, const int wid) {
;     ...
;         for (int t = 0; t < nt; t += 2) {
;     ...
;             PG8_LDA(At, 1, 1); PG8_STAGE(PG8_SB(1, 0), b3, voffB); PG8_STAGE(PG8_SB(1, 1), b3 + hstep, voffB); PG8_STAGE(PG8_SA(1, 0), a3, voffA);
;             PG8_WAIT_V(8); PG8_WAIT_L(0); PG8_BAR; PG8_MMA(1, 0, At, B0); PG8_MMA(1, 1, At, B1); PG8_BAR; PG8_SCHED;
	s_add_i32 s36, s54, s42
	v_lshl_add_u64 v[146:147], v[146:147], 0, s[58:59]
	s_mov_b32 m0, s36
	ds_read_b128 v[180:183], v150 offset:49152
	ds_read_b128 v[184:187], v150 offset:50176
	ds_read_b128 v[188:191], v150 offset:51200
	ds_read_b128 v[192:195], v150 offset:52224
	ds_read_b128 v[212:215], v150 offset:53248
	ds_read_b128 v[216:219], v150 offset:54272
	ds_read_b128 v[220:223], v150 offset:55296
	ds_read_b128 v[224:227], v150 offset:56320
	global_load_lds_dwordx4 v[146:147], off
	s_add_i32 m0, s36, 0x2000
	s_add_u32 s34, s34, 0x80080
	v_lshl_add_u64 v[146:147], v[200:201], 0, s[58:59]
	s_addc_u32 s35, s35, 0
	s_add_i32 s36, s55, s42
	global_load_lds_dwordx4 v[146:147], off
	v_lshl_add_u64 v[146:147], s[34:35], 0, v[134:135]
	s_mov_b32 m0, s36
	s_nop 0
	global_load_lds_dwordx4 v[146:147], off
	v_lshl_add_u64 v[146:147], s[34:35], 0, v[130:131]
	s_add_i32 m0, s36, 0x2000
	s_nop 0
	global_load_lds_dwordx4 v[146:147], off
	v_lshl_add_u64 v[146:147], v[202:203], 0, s[58:59]
	s_mov_b32 m0, s84
	s_nop 0
	global_load_lds_dwordx4 v[146:147], off
	v_lshl_add_u64 v[146:147], v[208:209], 0, s[58:59]
	s_mov_b32 m0, s85
	s_nop 0
	global_load_lds_dwordx4 v[146:147], off
	s_add_i32 s50, s50, 2
	s_add_u32 s30, s30, 0x100
	s_addc_u32 s31, s31, 0
	s_add_u32 s46, s46, 0x100
	s_addc_u32 s47, s47, 0
	s_cmp_gt_u32 s50, 29
	s_waitcnt vmcnt(8)
	s_waitcnt lgkmcnt(0)
	s_barrier
	s_setprio 1
	s_waitcnt lgkmcnt(0)
	v_mfma_f32_16x16x32_bf16 v[62:65], v[142:145], v[180:183], v[62:65]
	v_mfma_f32_16x16x32_bf16 v[58:61], v[156:159], v[180:183], v[58:61]
	v_mfma_f32_16x16x32_bf16 v[46:49], v[142:145], v[188:191], v[46:49]
	v_mfma_f32_16x16x32_bf16 v[42:45], v[156:159], v[188:191], v[42:45]
	v_mfma_f32_16x16x32_bf16 v[30:33], v[142:145], v[212:215], v[30:33]
	v_mfma_f32_16x16x32_bf16 v[26:29], v[156:159], v[212:215], v[26:29]
	v_mfma_f32_16x16x32_bf16 v[14:17], v[142:145], v[220:223], v[14:17]
	v_mfma_f32_16x16x32_bf16 v[10:13], v[156:159], v[220:223], v[10:13]
	v_mfma_f32_16x16x32_bf16 v[62:65], v[152:155], v[184:187], v[62:65]
	v_mfma_f32_16x16x32_bf16 v[58:61], v[160:163], v[184:187], v[58:61]
	v_mfma_f32_16x16x32_bf16 v[46:49], v[152:155], v[192:195], v[46:49]
	v_mfma_f32_16x16x32_bf16 v[42:45], v[160:163], v[192:195], v[42:45]
	v_mfma_f32_16x16x32_bf16 v[30:33], v[152:155], v[216:219], v[30:33]
	v_mfma_f32_16x16x32_bf16 v[26:29], v[160:163], v[216:219], v[26:29]
	v_mfma_f32_16x16x32_bf16 v[14:17], v[152:155], v[224:227], v[14:17]
	v_mfma_f32_16x16x32_bf16 v[10:13], v[160:163], v[224:227], v[10:13]
	s_setprio 0
	s_setprio 1
	v_mfma_f32_16x16x32_bf16 v[54:57], v[164:167], v[180:183], v[54:57]
	v_mfma_f32_16x16x32_bf16 v[50:53], v[172:175], v[180:183], v[50:53]
	v_mfma_f32_16x16x32_bf16 v[38:41], v[164:167], v[188:191], v[38:41]
	v_mfma_f32_16x16x32_bf16 v[34:37], v[172:175], v[188:191], v[34:37]
	v_mfma_f32_16x16x32_bf16 v[22:25], v[164:167], v[212:215], v[22:25]
	v_mfma_f32_16x16x32_bf16 v[18:21], v[172:175], v[212:215], v[18:21]
	v_mfma_f32_16x16x32_bf16 v[6:9], v[164:167], v[220:223], v[6:9]
	v_mfma_f32_16x16x32_bf16 v[2:5], v[172:175], v[220:223], v[2:5]
	v_mfma_f32_16x16x32_bf16 v[54:57], v[168:171], v[184:187], v[54:57]
	v_mfma_f32_16x16x32_bf16 v[50:53], v[176:179], v[184:187], v[50:53]
	v_mfma_f32_16x16x32_bf16 v[38:41], v[168:171], v[192:195], v[38:41]
	v_mfma_f32_16x16x32_bf16 v[34:37], v[176:179], v[192:195], v[34:37]
	v_mfma_f32_16x16x32_bf16 v[22:25], v[168:171], v[216:219], v[22:25]
	v_mfma_f32_16x16x32_bf16 v[18:21], v[176:179], v[216:219], v[18:21]
	v_mfma_f32_16x16x32_bf16 v[6:9], v[168:171], v[224:227], v[6:9]
	v_mfma_f32_16x16x32_bf16 v[2:5], v[176:179], v[224:227], v[2:5]
	s_setprio 0
	s_barrier
	s_cbranch_scc0 .LBB0_634
	s_and_b64 vcc, exec, s[16:17]
	s_cbranch_vccz .LBB0_637
	s_barrier
